# snake MFMA order + nt (streaming) stores for the gate/up GEMM H output
# speedup vs baseline: 1.0011x; 1.0011x over previous
.LBB0_724:
	v_mul_f32_e32 v147, 0xbfb8aa3b, v126
	v_exp_f32_e32 v147, v147
	v_lshl_add_u32 v148, s46, 7, v144
	v_lshl_add_u32 v146, s47, 8, v142
	v_ashrrev_i32_e32 v149, 31, v148
	v_add_f32_e32 v147, 1.0, v147
	v_rcp_f32_e32 v147, v147
	v_mov_b64_e32 v[140:141], s[10:11]
	s_movk_i32 s5, 0x5600
	v_mad_i64_i32 v[150:151], s[16:17], v146, s5, v[140:141]
	v_mul_f32_e32 v126, v126, v147
	v_mul_f32_e32 v122, v126, v122
	v_mul_f32_e32 v126, 0xbfb8aa3b, v127
	v_exp_f32_e32 v126, v126
	s_andn2_b64 vcc, exec, s[38:39]
	v_add_f32_e32 v126, 1.0, v126
	v_rcp_f32_e32 v126, v126
	s_nop 0
	v_mul_f32_e32 v126, v127, v126
	v_mul_f32_e32 v123, v126, v123
	v_mul_f32_e32 v126, 0xbfb8aa3b, v128
	v_exp_f32_e32 v126, v126
	s_nop 0
	v_add_f32_e32 v126, 1.0, v126
	v_rcp_f32_e32 v126, v126
	s_nop 0
	v_mul_f32_e32 v126, v128, v126
	v_mul_f32_e32 v124, v126, v124
	v_mul_f32_e32 v126, 0xbfb8aa3b, v129
	v_exp_f32_e32 v126, v126
	s_nop 0
	v_add_f32_e32 v126, 1.0, v126
	v_rcp_f32_e32 v126, v126
	s_nop 0
	v_mul_f32_e32 v126, v129, v126
	v_mul_f32_e32 v125, v126, v125
	v_mul_f32_e32 v126, 0xbfb8aa3b, v118
	v_exp_f32_e32 v126, v126
	s_nop 0
	v_add_f32_e32 v126, 1.0, v126
	v_rcp_f32_e32 v126, v126
	s_nop 0
	v_mul_f32_e32 v118, v118, v126
	v_mul_f32_e32 v118, v118, v114
	v_mul_f32_e32 v114, 0xbfb8aa3b, v119
	v_exp_f32_e32 v114, v114
	s_nop 0
	v_add_f32_e32 v114, 1.0, v114
	v_rcp_f32_e32 v114, v114
	s_nop 0
	v_mul_f32_e32 v114, v119, v114
	v_mul_f32_e32 v119, v114, v115
	v_mul_f32_e32 v114, 0xbfb8aa3b, v120
	v_exp_f32_e32 v114, v114
	s_nop 0
	v_add_f32_e32 v114, 1.0, v114
	v_rcp_f32_e32 v114, v114
	s_nop 0
	v_mul_f32_e32 v114, v120, v114
	v_mul_f32_e32 v126, v114, v116
	v_mul_f32_e32 v114, 0xbfb8aa3b, v121
	v_exp_f32_e32 v114, v114
	v_cvt_pk_bf16_f32 v116, v122, v123
	s_nop 0
	v_add_f32_e32 v114, 1.0, v114
	v_rcp_f32_e32 v114, v114
	s_nop 0
	v_mul_f32_e32 v114, v121, v114
	v_mul_f32_e32 v127, v114, v117
	v_lshlrev_b64 v[114:115], 1, v[148:149]
	v_lshl_add_u64 v[120:121], v[150:151], 0, v[114:115]
	v_cvt_pk_bf16_f32 v117, v124, v125
	v_cvt_pk_bf16_f32 v118, v118, v119
	v_cvt_pk_bf16_f32 v119, v126, v127
	global_store_dwordx4 v[120:121], v[116:119], off nt
	s_nop 1
	v_mul_f32_e32 v118, 0xbfb8aa3b, v110
	v_exp_f32_e32 v118, v118
	v_or_b32_e32 v116, 16, v146
	v_mad_i64_i32 v[116:117], s[16:17], v116, s5, v[140:141]
	v_add_f32_e32 v118, 1.0, v118
	v_rcp_f32_e32 v118, v118
	s_nop 0
	v_mul_f32_e32 v110, v110, v118
	v_mul_f32_e32 v106, v110, v106
	v_mul_f32_e32 v110, 0xbfb8aa3b, v111
	v_exp_f32_e32 v110, v110
	s_nop 0
	v_add_f32_e32 v110, 1.0, v110
	v_rcp_f32_e32 v110, v110
	s_nop 0
	v_mul_f32_e32 v110, v111, v110
	v_mul_f32_e32 v107, v110, v107
	v_mul_f32_e32 v110, 0xbfb8aa3b, v112
	v_exp_f32_e32 v110, v110
	s_nop 0
	v_add_f32_e32 v110, 1.0, v110
	v_rcp_f32_e32 v110, v110
	s_nop 0
	v_mul_f32_e32 v110, v112, v110
	v_mul_f32_e32 v108, v110, v108
	v_mul_f32_e32 v110, 0xbfb8aa3b, v113
	v_exp_f32_e32 v110, v110
	s_nop 0
	v_add_f32_e32 v110, 1.0, v110
	v_rcp_f32_e32 v110, v110
	s_nop 0
	v_mul_f32_e32 v110, v113, v110
	v_mul_f32_e32 v109, v110, v109
	v_mul_f32_e32 v110, 0xbfb8aa3b, v102
	v_exp_f32_e32 v110, v110
	s_nop 0
	v_add_f32_e32 v110, 1.0, v110
	v_rcp_f32_e32 v110, v110
	s_nop 0
	v_mul_f32_e32 v102, v102, v110
	v_mul_f32_e32 v110, v102, v98
	v_mul_f32_e32 v98, 0xbfb8aa3b, v103
	v_exp_f32_e32 v98, v98
	s_nop 0
	v_add_f32_e32 v98, 1.0, v98
	v_rcp_f32_e32 v98, v98
	s_nop 0
	v_mul_f32_e32 v98, v103, v98
	v_mul_f32_e32 v111, v98, v99
	v_mul_f32_e32 v98, 0xbfb8aa3b, v104
	v_exp_f32_e32 v98, v98
	v_lshl_add_u64 v[102:103], v[116:117], 0, v[114:115]
	v_add_f32_e32 v98, 1.0, v98
	v_rcp_f32_e32 v98, v98
	s_nop 0
	v_mul_f32_e32 v98, v104, v98
	v_mul_f32_e32 v104, v98, v100
	v_mul_f32_e32 v98, 0xbfb8aa3b, v105
	v_exp_f32_e32 v98, v98
	s_nop 0
	v_add_f32_e32 v98, 1.0, v98
	v_rcp_f32_e32 v98, v98
	s_nop 0
	v_mul_f32_e32 v98, v105, v98
	v_mul_f32_e32 v101, v98, v101
	v_cvt_pk_bf16_f32 v98, v106, v107
	v_cvt_pk_bf16_f32 v99, v108, v109
	v_cvt_pk_bf16_f32 v100, v110, v111
	v_cvt_pk_bf16_f32 v101, v104, v101
	global_store_dwordx4 v[102:103], v[98:101], off nt
	s_nop 1
	v_mul_f32_e32 v100, 0xbfb8aa3b, v94
	v_exp_f32_e32 v100, v100
	v_or_b32_e32 v98, 32, v146
	v_mad_i64_i32 v[98:99], s[16:17], v98, s5, v[140:141]
	v_add_f32_e32 v100, 1.0, v100
	v_rcp_f32_e32 v100, v100
	s_nop 0
	v_mul_f32_e32 v94, v94, v100
	v_mul_f32_e32 v90, v94, v90
	v_mul_f32_e32 v94, 0xbfb8aa3b, v95
	v_exp_f32_e32 v94, v94
	s_nop 0
	v_add_f32_e32 v94, 1.0, v94
	v_rcp_f32_e32 v94, v94
	s_nop 0
	v_mul_f32_e32 v94, v95, v94
	v_mul_f32_e32 v91, v94, v91
	v_mul_f32_e32 v94, 0xbfb8aa3b, v96
	v_exp_f32_e32 v94, v94
	s_nop 0
	v_add_f32_e32 v94, 1.0, v94
	v_rcp_f32_e32 v94, v94
	s_nop 0
	v_mul_f32_e32 v94, v96, v94
	v_mul_f32_e32 v92, v94, v92
	v_mul_f32_e32 v94, 0xbfb8aa3b, v97
	v_exp_f32_e32 v94, v94
	s_nop 0
	v_add_f32_e32 v94, 1.0, v94
	v_rcp_f32_e32 v94, v94
	s_nop 0
	v_mul_f32_e32 v94, v97, v94
	v_mul_f32_e32 v93, v94, v93
	v_mul_f32_e32 v94, 0xbfb8aa3b, v86
	v_exp_f32_e32 v94, v94
	s_nop 0
	v_add_f32_e32 v94, 1.0, v94
	v_rcp_f32_e32 v94, v94
	s_nop 0
	v_mul_f32_e32 v86, v86, v94
	v_mul_f32_e32 v94, v86, v82
	v_mul_f32_e32 v82, 0xbfb8aa3b, v87
	v_exp_f32_e32 v82, v82
	s_nop 0
	v_add_f32_e32 v82, 1.0, v82
	v_rcp_f32_e32 v82, v82
	s_nop 0
	v_mul_f32_e32 v82, v87, v82
	v_mul_f32_e32 v95, v82, v83
	v_mul_f32_e32 v82, 0xbfb8aa3b, v88
	v_exp_f32_e32 v82, v82
	v_lshl_add_u64 v[86:87], v[98:99], 0, v[114:115]
	v_add_f32_e32 v82, 1.0, v82
	v_rcp_f32_e32 v82, v82
	s_nop 0
	v_mul_f32_e32 v82, v88, v82
	v_mul_f32_e32 v88, v82, v84
	v_mul_f32_e32 v82, 0xbfb8aa3b, v89
	v_exp_f32_e32 v82, v82
	s_nop 0
	v_add_f32_e32 v82, 1.0, v82
	v_rcp_f32_e32 v82, v82
	s_nop 0
	v_mul_f32_e32 v82, v89, v82
	v_mul_f32_e32 v85, v82, v85
	v_cvt_pk_bf16_f32 v82, v90, v91
	v_cvt_pk_bf16_f32 v83, v92, v93
	v_cvt_pk_bf16_f32 v84, v94, v95
	v_cvt_pk_bf16_f32 v85, v88, v85
	global_store_dwordx4 v[86:87], v[82:85], off nt
	s_nop 1
	v_mul_f32_e32 v84, 0xbfb8aa3b, v78
	v_exp_f32_e32 v84, v84
	v_or_b32_e32 v82, 48, v146
	v_mad_i64_i32 v[82:83], s[16:17], v82, s5, v[140:141]
	v_add_f32_e32 v84, 1.0, v84
	v_rcp_f32_e32 v84, v84
	s_nop 0
	v_mul_f32_e32 v78, v78, v84
	v_mul_f32_e32 v74, v78, v74
	v_mul_f32_e32 v78, 0xbfb8aa3b, v79
	v_exp_f32_e32 v78, v78
	s_nop 0
	v_add_f32_e32 v78, 1.0, v78
	v_rcp_f32_e32 v78, v78
	s_nop 0
	v_mul_f32_e32 v78, v79, v78
	v_mul_f32_e32 v75, v78, v75
	v_mul_f32_e32 v78, 0xbfb8aa3b, v80
	v_exp_f32_e32 v78, v78
	s_nop 0
	v_add_f32_e32 v78, 1.0, v78
	v_rcp_f32_e32 v78, v78
	s_nop 0
	v_mul_f32_e32 v78, v80, v78
	v_mul_f32_e32 v76, v78, v76
	v_mul_f32_e32 v78, 0xbfb8aa3b, v81
	v_exp_f32_e32 v78, v78
	s_nop 0
	v_add_f32_e32 v78, 1.0, v78
	v_rcp_f32_e32 v78, v78
	s_nop 0
	v_mul_f32_e32 v78, v81, v78
	v_mul_f32_e32 v77, v78, v77
	v_mul_f32_e32 v78, 0xbfb8aa3b, v70
	v_exp_f32_e32 v78, v78
	s_nop 0
	v_add_f32_e32 v78, 1.0, v78
	v_rcp_f32_e32 v78, v78
	s_nop 0
	v_mul_f32_e32 v70, v70, v78
	v_mul_f32_e32 v78, v70, v66
	v_mul_f32_e32 v66, 0xbfb8aa3b, v71
	v_exp_f32_e32 v66, v66
	s_nop 0
	v_add_f32_e32 v66, 1.0, v66
	v_rcp_f32_e32 v66, v66
	s_nop 0
	v_mul_f32_e32 v66, v71, v66
	v_mul_f32_e32 v79, v66, v67
	v_mul_f32_e32 v66, 0xbfb8aa3b, v72
	v_exp_f32_e32 v66, v66
	v_lshl_add_u64 v[70:71], v[82:83], 0, v[114:115]
	v_add_f32_e32 v66, 1.0, v66
	v_rcp_f32_e32 v66, v66
	s_nop 0
	v_mul_f32_e32 v66, v72, v66
	v_mul_f32_e32 v72, v66, v68
	v_mul_f32_e32 v66, 0xbfb8aa3b, v73
	v_exp_f32_e32 v66, v66
	s_nop 0
	v_add_f32_e32 v66, 1.0, v66
	v_rcp_f32_e32 v66, v66
	s_nop 0
	v_mul_f32_e32 v66, v73, v66
	v_mul_f32_e32 v69, v66, v69
	v_cvt_pk_bf16_f32 v66, v74, v75
	v_cvt_pk_bf16_f32 v67, v76, v77
	v_cvt_pk_bf16_f32 v68, v78, v79
	v_cvt_pk_bf16_f32 v69, v72, v69
	global_store_dwordx4 v[70:71], v[66:69], off nt
	s_nop 1
	v_mul_f32_e32 v68, 0xbfb8aa3b, v62
	v_exp_f32_e32 v68, v68
	v_add_u32_e32 v66, 0x80, v146
	v_mad_i64_i32 v[66:67], s[16:17], v66, s5, v[140:141]
	v_add_f32_e32 v68, 1.0, v68
	v_rcp_f32_e32 v68, v68
	s_nop 0
	v_mul_f32_e32 v62, v62, v68
	v_mul_f32_e32 v58, v62, v58
	v_mul_f32_e32 v62, 0xbfb8aa3b, v63
	v_exp_f32_e32 v62, v62
	s_nop 0
	v_add_f32_e32 v62, 1.0, v62
	v_rcp_f32_e32 v62, v62
	s_nop 0
	v_mul_f32_e32 v62, v63, v62
	v_mul_f32_e32 v59, v62, v59
	v_mul_f32_e32 v62, 0xbfb8aa3b, v64
	v_exp_f32_e32 v62, v62
	s_nop 0
	v_add_f32_e32 v62, 1.0, v62
	v_rcp_f32_e32 v62, v62
	s_nop 0
	v_mul_f32_e32 v62, v64, v62
	v_mul_f32_e32 v60, v62, v60
	v_mul_f32_e32 v62, 0xbfb8aa3b, v65
	v_exp_f32_e32 v62, v62
	s_nop 0
	v_add_f32_e32 v62, 1.0, v62
	v_rcp_f32_e32 v62, v62
	s_nop 0
	v_mul_f32_e32 v62, v65, v62
	v_mul_f32_e32 v61, v62, v61
	v_mul_f32_e32 v62, 0xbfb8aa3b, v54
	v_exp_f32_e32 v62, v62
	s_nop 0
	v_add_f32_e32 v62, 1.0, v62
	v_rcp_f32_e32 v62, v62
	s_nop 0
	v_mul_f32_e32 v54, v54, v62
	v_mul_f32_e32 v62, v54, v50
	v_mul_f32_e32 v50, 0xbfb8aa3b, v55
	v_exp_f32_e32 v50, v50
	s_nop 0
	v_add_f32_e32 v50, 1.0, v50
	v_rcp_f32_e32 v50, v50
	s_nop 0
	v_mul_f32_e32 v50, v55, v50
	v_mul_f32_e32 v63, v50, v51
	v_mul_f32_e32 v50, 0xbfb8aa3b, v56
	v_exp_f32_e32 v50, v50
	v_lshl_add_u64 v[54:55], v[66:67], 0, v[114:115]
	v_add_f32_e32 v50, 1.0, v50
	v_rcp_f32_e32 v50, v50
	s_nop 0
	v_mul_f32_e32 v50, v56, v50
	v_mul_f32_e32 v56, v50, v52
	v_mul_f32_e32 v50, 0xbfb8aa3b, v57
	v_exp_f32_e32 v50, v50
	s_nop 0
	v_add_f32_e32 v50, 1.0, v50
	v_rcp_f32_e32 v50, v50
	s_nop 0
	v_mul_f32_e32 v50, v57, v50
	v_mul_f32_e32 v53, v50, v53
	v_cvt_pk_bf16_f32 v50, v58, v59
	v_cvt_pk_bf16_f32 v51, v60, v61
	v_cvt_pk_bf16_f32 v52, v62, v63
	v_cvt_pk_bf16_f32 v53, v56, v53
	global_store_dwordx4 v[54:55], v[50:53], off nt
	s_nop 1
	v_mul_f32_e32 v52, 0xbfb8aa3b, v46
	v_exp_f32_e32 v52, v52
	v_add_u32_e32 v50, 0x90, v146
	v_mad_i64_i32 v[50:51], s[16:17], v50, s5, v[140:141]
	v_add_f32_e32 v52, 1.0, v52
	v_rcp_f32_e32 v52, v52
	s_nop 0
	v_mul_f32_e32 v46, v46, v52
	v_mul_f32_e32 v42, v46, v42
	v_mul_f32_e32 v46, 0xbfb8aa3b, v47
	v_exp_f32_e32 v46, v46
	s_nop 0
	v_add_f32_e32 v46, 1.0, v46
	v_rcp_f32_e32 v46, v46
	s_nop 0
	v_mul_f32_e32 v46, v47, v46
	v_mul_f32_e32 v43, v46, v43
	v_mul_f32_e32 v46, 0xbfb8aa3b, v48
	v_exp_f32_e32 v46, v46
	s_nop 0
	v_add_f32_e32 v46, 1.0, v46
	v_rcp_f32_e32 v46, v46
	s_nop 0
	v_mul_f32_e32 v46, v48, v46
	v_mul_f32_e32 v44, v46, v44
	v_mul_f32_e32 v46, 0xbfb8aa3b, v49
	v_exp_f32_e32 v46, v46
	s_nop 0
	v_add_f32_e32 v46, 1.0, v46
	v_rcp_f32_e32 v46, v46
	s_nop 0
	v_mul_f32_e32 v46, v49, v46
	v_mul_f32_e32 v45, v46, v45
	v_mul_f32_e32 v46, 0xbfb8aa3b, v38
	v_exp_f32_e32 v46, v46
	s_nop 0
	v_add_f32_e32 v46, 1.0, v46
	v_rcp_f32_e32 v46, v46
	s_nop 0
	v_mul_f32_e32 v38, v38, v46
	v_mul_f32_e32 v46, v38, v34
	v_mul_f32_e32 v34, 0xbfb8aa3b, v39
	v_exp_f32_e32 v34, v34
	s_nop 0
	v_add_f32_e32 v34, 1.0, v34
	v_rcp_f32_e32 v34, v34
	s_nop 0
	v_mul_f32_e32 v34, v39, v34
	v_mul_f32_e32 v47, v34, v35
	v_mul_f32_e32 v34, 0xbfb8aa3b, v40
	v_exp_f32_e32 v34, v34
	v_lshl_add_u64 v[38:39], v[50:51], 0, v[114:115]
	v_add_f32_e32 v34, 1.0, v34
	v_rcp_f32_e32 v34, v34
	s_nop 0
	v_mul_f32_e32 v34, v40, v34
	v_mul_f32_e32 v40, v34, v36
	v_mul_f32_e32 v34, 0xbfb8aa3b, v41
	v_exp_f32_e32 v34, v34
	s_nop 0
	v_add_f32_e32 v34, 1.0, v34
	v_rcp_f32_e32 v34, v34
	s_nop 0
	v_mul_f32_e32 v34, v41, v34
	v_mul_f32_e32 v37, v34, v37
	v_cvt_pk_bf16_f32 v34, v42, v43
	v_cvt_pk_bf16_f32 v35, v44, v45
	v_cvt_pk_bf16_f32 v36, v46, v47
	v_cvt_pk_bf16_f32 v37, v40, v37
	global_store_dwordx4 v[38:39], v[34:37], off nt
	s_nop 1
	v_mul_f32_e32 v36, 0xbfb8aa3b, v30
	v_exp_f32_e32 v36, v36
	v_add_u32_e32 v34, 0xa0, v146
	v_mad_i64_i32 v[34:35], s[16:17], v34, s5, v[140:141]
	v_add_f32_e32 v36, 1.0, v36
	v_rcp_f32_e32 v36, v36
	s_nop 0
	v_mul_f32_e32 v30, v30, v36
	v_mul_f32_e32 v26, v30, v26
	v_mul_f32_e32 v30, 0xbfb8aa3b, v31
	v_exp_f32_e32 v30, v30
	s_nop 0
	v_add_f32_e32 v30, 1.0, v30
	v_rcp_f32_e32 v30, v30
	s_nop 0
	v_mul_f32_e32 v30, v31, v30
	v_mul_f32_e32 v27, v30, v27
	v_mul_f32_e32 v30, 0xbfb8aa3b, v32
	v_exp_f32_e32 v30, v30
	s_nop 0
	v_add_f32_e32 v30, 1.0, v30
	v_rcp_f32_e32 v30, v30
	s_nop 0
	v_mul_f32_e32 v30, v32, v30
	v_mul_f32_e32 v28, v30, v28
	v_mul_f32_e32 v30, 0xbfb8aa3b, v33
	v_exp_f32_e32 v30, v30
	s_nop 0
	v_add_f32_e32 v30, 1.0, v30
	v_rcp_f32_e32 v30, v30
	s_nop 0
	v_mul_f32_e32 v30, v33, v30
	v_mul_f32_e32 v29, v30, v29
	v_mul_f32_e32 v30, 0xbfb8aa3b, v22
	v_exp_f32_e32 v30, v30
	s_nop 0
	v_add_f32_e32 v30, 1.0, v30
	v_rcp_f32_e32 v30, v30
	s_nop 0
	v_mul_f32_e32 v22, v22, v30
	v_mul_f32_e32 v30, v22, v18
	v_mul_f32_e32 v18, 0xbfb8aa3b, v23
	v_exp_f32_e32 v18, v18
	s_nop 0
	v_add_f32_e32 v18, 1.0, v18
	v_rcp_f32_e32 v18, v18
	s_nop 0
	v_mul_f32_e32 v18, v23, v18
	v_mul_f32_e32 v31, v18, v19
	v_mul_f32_e32 v18, 0xbfb8aa3b, v24
	v_exp_f32_e32 v18, v18
	v_lshl_add_u64 v[22:23], v[34:35], 0, v[114:115]
	v_add_f32_e32 v18, 1.0, v18
	v_rcp_f32_e32 v18, v18
	s_nop 0
	v_mul_f32_e32 v18, v24, v18
	v_mul_f32_e32 v24, v18, v20
	v_mul_f32_e32 v18, 0xbfb8aa3b, v25
	v_exp_f32_e32 v18, v18
	s_nop 0
	v_add_f32_e32 v18, 1.0, v18
	v_rcp_f32_e32 v18, v18
	s_nop 0
	v_mul_f32_e32 v18, v25, v18
	v_mul_f32_e32 v21, v18, v21
	v_cvt_pk_bf16_f32 v18, v26, v27
	v_cvt_pk_bf16_f32 v19, v28, v29
	v_cvt_pk_bf16_f32 v20, v30, v31
	v_cvt_pk_bf16_f32 v21, v24, v21
	global_store_dwordx4 v[22:23], v[18:21], off nt
	s_nop 1
	v_mul_f32_e32 v20, 0xbfb8aa3b, v14
	v_exp_f32_e32 v20, v20
	v_add_u32_e32 v18, 0xb0, v146
	v_mad_i64_i32 v[18:19], s[16:17], v18, s5, v[140:141]
	v_add_f32_e32 v20, 1.0, v20
	v_rcp_f32_e32 v20, v20
	s_mov_b64 s[16:17], -1
	v_mul_f32_e32 v14, v14, v20
	v_mul_f32_e32 v10, v14, v10
	v_mul_f32_e32 v14, 0xbfb8aa3b, v15
	v_exp_f32_e32 v14, v14
	s_nop 0
	v_add_f32_e32 v14, 1.0, v14
	v_rcp_f32_e32 v14, v14
	s_nop 0
	v_mul_f32_e32 v14, v15, v14
	v_mul_f32_e32 v11, v14, v11
	v_mul_f32_e32 v14, 0xbfb8aa3b, v16
	v_exp_f32_e32 v14, v14
	s_nop 0
	v_add_f32_e32 v14, 1.0, v14
	v_rcp_f32_e32 v14, v14
	s_nop 0
	v_mul_f32_e32 v14, v16, v14
	v_mul_f32_e32 v12, v14, v12
	v_mul_f32_e32 v14, 0xbfb8aa3b, v17
	v_exp_f32_e32 v14, v14
	s_nop 0
	v_add_f32_e32 v14, 1.0, v14
	v_rcp_f32_e32 v14, v14
	s_nop 0
	v_mul_f32_e32 v14, v17, v14
	v_mul_f32_e32 v13, v14, v13
	v_mul_f32_e32 v14, 0xbfb8aa3b, v6
	v_exp_f32_e32 v14, v14
	s_nop 0
	v_add_f32_e32 v14, 1.0, v14
	v_rcp_f32_e32 v14, v14
	s_nop 0
	v_mul_f32_e32 v6, v6, v14
	v_mul_f32_e32 v14, v6, v2
	v_mul_f32_e32 v2, 0xbfb8aa3b, v7
	v_exp_f32_e32 v2, v2
	s_nop 0
	v_add_f32_e32 v2, 1.0, v2
	v_rcp_f32_e32 v2, v2
	s_nop 0
	v_mul_f32_e32 v2, v7, v2
	v_mul_f32_e32 v15, v2, v3
	v_mul_f32_e32 v2, 0xbfb8aa3b, v8
	v_exp_f32_e32 v2, v2
	v_lshl_add_u64 v[6:7], v[18:19], 0, v[114:115]
	v_add_f32_e32 v2, 1.0, v2
	v_rcp_f32_e32 v2, v2
	s_nop 0
	v_mul_f32_e32 v2, v8, v2
	v_mul_f32_e32 v8, v2, v4
	v_mul_f32_e32 v2, 0xbfb8aa3b, v9
	v_exp_f32_e32 v2, v2
	s_nop 0
	v_add_f32_e32 v2, 1.0, v2
	v_rcp_f32_e32 v2, v2
	s_nop 0
	v_mul_f32_e32 v2, v9, v2
	v_mul_f32_e32 v5, v2, v5
	v_cvt_pk_bf16_f32 v2, v10, v11
	v_cvt_pk_bf16_f32 v3, v12, v13
	v_cvt_pk_bf16_f32 v4, v14, v15
	v_cvt_pk_bf16_f32 v5, v8, v5
	global_store_dwordx4 v[6:7], v[2:5], off nt
	s_cbranch_vccnz .LBB0_717
	s_andn2_b64 vcc, exec, s[0:1]
	s_cbranch_vccnz .LBB0_716
	s_barrier
	s_branch .LBB0_716
